# baseline (speedup 1.0000x reference)
; DI int my_tid() { int t = threadIdx.x; asm volatile("" : "+v"(t)); return t; }
; DI void phase_mixers(int l_, unsigned* ctr, LAS unsigned char* lds) {
;     ...
;   for (;;) {
;     __syncthreads();
;     if (my_tid() == 0) *slot = nxt;
;     __syncthreads();
;     const int it = __builtin_amdgcn_readfirstlane(*slot);
;     if (it >= NIT) break;
;     if (my_tid() == 0) nxt = (int)__hip_atomic_fetch_add(ctr, 1u, __ATOMIC_RELAXED, __HIP_MEMORY_SCOPE_AGENT);
;     int r = it; { int lv = l; asm volatile("" : "+v"(lv)); l = __builtin_amdgcn_readfirstlane(lv); }
;     const __attribute__((address_space(4))) void* kpi = (const __attribute__((address_space(4))) void*)__builtin_amdgcn_kernarg_segment_ptr();
;     asm volatile("" : "+s"(kpi));
;     CP& p = *(CP*)kpi;
;     if (r < N_MEM) { mix_mem(p, l, r, lds); continue; } r -= N_MEM;
;     if (r < N_SB) { mix_sb(p, l, r, lds); continue; } r -= N_SB;
;     if (r < N_G) { mix_gmlp(p, l, r, lds); continue; } r -= N_G;
;     if (r < N_C) { mix_conv(p, l, r, lds); continue; }
.LBB0_119:
	v_mov_b32_e32 v1, v144
	s_waitcnt vmcnt(0) lgkmcnt(0)
	s_barrier
	s_nop 0
	v_cmp_eq_u32_e32 vcc, 0, v1
	s_and_saveexec_b64 s[8:9], vcc
	v_mov_b32_e32 v1, s95
	ds_write_b32 v1, v134
	s_or_b64 exec, exec, s[8:9]
	v_mov_b32_e32 v1, s95
	s_waitcnt lgkmcnt(0)
	s_barrier
	ds_read_b32 v1, v1
	s_waitcnt lgkmcnt(0)
	v_readfirstlane_b32 s74, v1
	s_cmpk_gt_i32 s74, 0x4d0
	s_cbranch_scc1 .LBB0_134
	s_movk_i32 s0, 0xfe6f
	s_cmpk_lt_i32 s74, 0x191
	s_cselect_b32 s0, 0x237, s0
	s_cmpk_lt_i32 s74, 0x109
	s_cselect_b32 s0, 0x3c7, s0
	s_cmpk_lt_i32 s74, 1
	s_cselect_b32 s0, 0x4d0, s0
	s_add_i32 s74, s74, s0
	v_mov_b32_e32 v1, v144
	s_nop 0
	v_cmp_eq_u32_e32 vcc, 0, v1
	s_and_saveexec_b64 s[8:9], vcc
	s_cbranch_execz .LBB0_126
	s_mov_b64 s[12:13], exec
	v_mbcnt_lo_u32_b32 v1, s12, 0
	v_mbcnt_hi_u32_b32 v1, s13, v1
	v_cmp_eq_u32_e32 vcc, 0, v1
	s_and_saveexec_b64 s[10:11], vcc
	s_cbranch_execz .LBB0_125
	s_bcnt1_i32_b64 s0, s[12:13]
	v_mov_b32_e32 v2, s0
	global_atomic_add v2, v147, v2, s[62:63] sc0
